# v14 + SWA unit head: sink-logit wait moved behind the second tile's LDS-DMA issue (one global round trip per unit instead of two)
# baseline (speedup 1.0000x reference)
; template <bool SWA> ...
;     ...
;     const int lane = tid & 63, l32 = lane & 31, hi = lane >> 5; const int wv = __builtin_amdgcn_readfirstlane(tid >> 6);
;     bf16x8 qf[ND];
; #pragma unroll
;     for (int d0 = 0; d0 < ND; ++d0) qf[d0] = *(const bf16x8*)(Qrow + 16 * d0 + 8 * hi);
;     const int pkey = (lane & ~12) | ((lane & 4) << 1) | ((lane & 8) >> 1);
;     const int koff = pkey * ldk + 8 * wv, voff = lane * T + 8 * wv, roff = pkey * 512 + 8 * (wv & 3);
;     const bool do_r = (!SWA) && wv < 4;
;     const int kfo = hi * 1024 + l32 * 16, vfo = AT_KB + hi * 1024 + l32 * 16;
;     ...
;     AT_GLOAD(0, 0); AT_GLOAD(1, AT_BUF);
;     asm volatile("s_waitcnt vmcnt(0)" ::: "memory");
;     __syncthreads();
;     f32x16 o0, o1, negm;
;     float mref = SWA ? m_init : 0.f, lrun = l_init;
; #pragma unroll
;     for (int r = 0; r < 16; ++r) { o0[r] = 0.f; o1[r] = 0.f; negm[r] = -mref; }
;     f32x16 sA0, sA1, sB0, sB1;
;     ...
;     {
;         const unsigned char* Bn = lds;
;         sA0 = __builtin_amdgcn_mfma_f32_32x32x16_bf16(*(const bf16x8*)(Bn + kfo), qf[0], negm, 0, 0, 0);
;         sA1 = __builtin_amdgcn_mfma_f32_32x32x16_bf16(*(const bf16x8*)(Bn + kfo + 512), qf[0], negm, 0, 0, 0);
; #pragma unroll
;         for (int d0 = 1; d0 < ND; ++d0) { sA0 = __builtin_amdgcn_mfma_f32_32x32x16_bf16(*(const bf16x8*)(Bn + kfo + 2048 * d0), qf[d0], sA0, 0, 0, 0);
;             sA1 = __builtin_amdgcn_mfma_f32_32x32x16_bf16(*(const bf16x8*)(Bn + kfo + 512 + 2048 * d0), qf[d0], sA1, 0, 0, 0); }
;         AT_MASK(sA0, sA1, 0);
; __global__ void __launch_bounds__(512, 2) mk_fwd(Args a) {
;     ...
;                     const int uu = u + k, hp = uu & 1, g2 = (uu >> 1) & 1, nblk = uu >> 2; const int row0 = nblk * 128;
;                     const int S_ = row0 < TP ? 4096 : 8192; const int base = row0 < TP ? (row0 & ~4095) : TP + ((row0 - TP) & ~8191);
;                     const int n = (row0 - base) >> 7; const int t_lo = n > 0 ? 2 * (n - 1) : 0; int t_hi = 2 * (n + 2); if (t_hi > S_ / 64) t_hi = S_ / 64;
;                     const int head = 4 * g2 + 2 * hp + (wv >> 2); const int qpos = 128 * n + 32 * (wv & 3) + l32; const size_t qrow = (size_t)base + qpos; const size_t kbase = (size_t)base + 64 * t_lo;
;                     attn_unit<true>(lds, ldsl, SWAQK + qrow * 768 + head * 64, SWAQK + kbase * 768 + 512 + g2 * 64, 768, SWAQK, SWAVT + (size_t)(g2 * 64) * T + kbase, t_hi - t_lo,
.LBB0_1057:
	s_lshl_b32 s26, s16, 1
	s_lshr_b32 s21, s16, 1
	s_and_b32 s26, s26, 2
	s_lshl_b32 s20, s21, 2
	s_add_i32 s26, s26, s19
	s_add_i32 s20, s26, s20
	s_lshl_b32 s26, s20, 6
	s_ashr_i32 s27, s26, 31
	s_lshl_b32 s92, s21, 6
	s_lshl_b32 s21, s21, 7
	s_add_u32 s36, s15, s21
	s_addc_u32 s37, s12, 0
	s_lshl_b64 s[28:29], s[92:93], 16
	s_add_u32 s38, s13, s28
	s_addc_u32 s39, s14, s29
	s_ashr_i32 s21, s20, 31
	s_lshl_b64 s[20:21], s[20:21], 2
	s_add_u32 s20, s3, s20
	s_addc_u32 s21, s18, s21
	global_load_dword v0, v1, s[20:21]
	v_lshl_add_u64 v[2:3], s[26:27], 1, v[178:179]
	flat_load_dwordx4 v[110:113], v[2:3]
	flat_load_dwordx4 v[102:105], v[2:3] offset:32
	flat_load_dwordx4 v[106:109], v[2:3] offset:64
	flat_load_dwordx4 v[98:101], v[2:3] offset:96
	v_readfirstlane_b32 s20, v230
	s_ashr_i32 s28, s20, 6
	s_lshl_b32 s20, s28, 3
	v_add_u32_e32 v80, s20, v186
	v_ashrrev_i32_e32 v81, 31, v80
	v_add_u32_e32 v2, s20, v231
	v_lshl_add_u64 v[4:5], v[80:81], 1, s[36:37]
	s_mov_b64 s[20:21], 0x400
	v_lshl_add_u64 v[6:7], v[4:5], 0, s[20:21]
	s_lshl_b32 s20, s28, 10
	s_add_i32 s31, s20, 0
	s_mov_b32 m0, s31
	v_ashrrev_i32_e32 v3, 31, v2
	global_load_lds_dwordx4 v[6:7], off
	v_lshl_add_u64 v[180:181], v[2:3], 1, s[38:39]
	s_add_i32 m0, s31, 0x3000
	s_mov_b64 s[20:21], 0x18400
	global_load_lds_dwordx4 v[180:181], off
	s_add_i32 m0, s31, 0x5000
	v_lshl_add_u64 v[2:3], v[4:5], 0, s[20:21]
	global_load_lds_dwordx4 v[2:3], off
	v_lshl_add_u64 v[2:3], v[180:181], 0, s[0:1]
	s_add_i32 m0, s31, 0x8000
	s_nop 0
	global_load_lds_dwordx4 v[2:3], off
	s_waitcnt vmcnt(0)
	s_waitcnt vmcnt(0) lgkmcnt(0)
	v_mul_f32_e32 v207, 0x3fb8aa3b, v0
	v_xor_b32_e32 v50, 0x80000000, v207
	s_barrier
	ds_read_b128 v[18:21], v187
	ds_read_b128 v[34:37], v187 offset:512
	v_mov_b32_e32 v51, v50
	v_mov_b32_e32 v52, v50
	v_mov_b32_e32 v53, v50
	v_mov_b32_e32 v54, v50
	v_mov_b32_e32 v55, v50
	v_mov_b32_e32 v56, v50
	v_mov_b32_e32 v57, v50
	v_mov_b32_e32 v58, v50
	v_mov_b32_e32 v59, v50
	v_mov_b32_e32 v60, v50
	v_mov_b32_e32 v61, v50
	v_mov_b32_e32 v62, v50
	v_mov_b32_e32 v63, v50
	v_mov_b32_e32 v64, v50
	v_mov_b32_e32 v65, v50
	s_cmp_gt_i32 s28, 3
	s_cselect_b64 s[20:21], -1, 0
	s_waitcnt lgkmcnt(1)
	v_mfma_f32_32x32x16_bf16 v[2:17], v[18:21], v[110:113], v[50:65]
	v_mov_b64_e32 v[18:19], v[50:51]
	v_mov_b64_e32 v[20:21], v[52:53]
	v_mov_b64_e32 v[22:23], v[54:55]
	v_mov_b64_e32 v[24:25], v[56:57]
	v_mov_b64_e32 v[26:27], v[58:59]
	v_mov_b64_e32 v[28:29], v[60:61]
	v_mov_b64_e32 v[30:31], v[62:63]
	v_mov_b64_e32 v[32:33], v[64:65]
	s_cmp_lt_i32 s28, 4
	s_waitcnt lgkmcnt(0)
	v_mfma_f32_32x32x16_bf16 v[18:33], v[34:37], v[110:113], v[18:33]
	ds_read_b128 v[34:37], v187 offset:2048
	s_waitcnt lgkmcnt(0)
	v_mfma_f32_32x32x16_bf16 v[2:17], v[34:37], v[102:105], v[2:17]
	ds_read_b128 v[34:37], v187 offset:2560
	s_waitcnt lgkmcnt(0)
	v_mfma_f32_32x32x16_bf16 v[18:33], v[34:37], v[102:105], v[18:33]
	ds_read_b128 v[34:37], v187 offset:4096
	s_waitcnt lgkmcnt(0)
	v_mfma_f32_32x32x16_bf16 v[2:17], v[34:37], v[106:109], v[2:17]
	ds_read_b128 v[34:37], v187 offset:4608
	s_waitcnt lgkmcnt(0)
	v_mfma_f32_32x32x16_bf16 v[18:33], v[34:37], v[106:109], v[18:33]
	ds_read_b128 v[34:37], v187 offset:6144
	s_waitcnt lgkmcnt(0)
	v_mfma_f32_32x32x16_bf16 v[2:17], v[34:37], v[98:101], v[2:17]
	ds_read_b128 v[34:37], v187 offset:6656
	s_waitcnt lgkmcnt(0)
	v_mfma_f32_32x32x16_bf16 v[18:33], v[34:37], v[98:101], v[18:33]
	s_cbranch_scc1 .LBB0_1059
	s_setprio 1
